# opt18: + inproj epilogue: cos/sin rows fetched two row-groups at a time (4 exposed round trips per tile instead of 8)
# baseline (speedup 1.0000x reference)
;     __device__ __forceinline__ void operator()(const f32x4 (&acc)[2][2][4][2], const Unit& u, int wr, int wc, int fr, int fq, PG8_LAS unsigned char* lds) const {
;     ...
;         for (int bj = 0; bj < 2; ++bj) {
;             const int slot = u.pn * 4 + bj * 2 + (wc >> 1);
;             isq[bj] = (slot < 4) || (slot >= 10 && slot < 16) || (slot >= 28 && slot < 34);
;             isk[bj] = slot == 4 || slot == 6 || slot == 8 || (slot >= 16 && slot < 22) || slot == 34 || slot == 35;
;             vi[bj] = -1;
;             if (slot == 7) vi[bj] = 0; else if (slot == 9) vi[bj] = 1; else if (slot >= 22 && slot < 28) vi[bj] = 2 + (slot - 22); else if (slot == 36 || slot == 37) vi[bj] = 8 + (slot - 36);
;             ki[bj] = -1;
;             if (slot == 6) ki[bj] = 0; else if (slot == 8) ki[bj] = 1; else if (slot >= 16 && slot < 22) ki[bj] = 2 + (slot - 16); else if (slot == 34 || slot == 35) ki[bj] = 8 + (slot - 34);
;             isg[bj] = slot == 38;
;             col0[bj] = slot * 64 + gsub * 32 + 8 * fq;
;         }
;         const bool anyrope = isq[0] || isk[0] || isq[1] || isk[1];
; #pragma unroll
;         for (int ai = 0; ai < 2; ++ai)
; #pragma unroll
;             for (int m = 0; m < 4; ++m) {
;                 const int row = row0 + ai * HALF + m * 16;
;                 f32x4 cs = {1.f, 1.f, 1.f, 1.f}, sn = {0.f, 0.f, 0.f, 0.f};
;                 if (anyrope) { cs = *(const f32x4*)(cosT + (size_t)row * 32 + 16 * gsub + 4 * fq); sn = *(const f32x4*)(sinT + (size_t)row * 32 + 16 * gsub + 4 * fq); }
.LBB0_203:
	s_or_b32 s20, s18, 2
	s_cmp_lt_i32 s20, 4
	s_cselect_b64 s[6:7], -1, 0
	s_add_i32 s9, s19, -8
	s_sub_i32 s16, s19, 26
	s_min_u32 s9, s9, s16
	s_cmp_lt_u32 s9, 6
	s_cselect_b64 s[16:17], -1, 0
	s_or_b64 s[12:13], s[14:15], s[12:13]
	s_lshl_b32 s35, s8, 8
	s_or_b64 s[6:7], s[16:17], s[6:7]
	s_or_b64 s[14:15], s[10:11], s[12:13]
	s_add_i32 s35, s35, s66
	s_cmp_lt_i32 s18, 4
	s_cselect_b64 s[8:9], -1, 0
	s_add_i32 s10, s19, -10
	s_sub_i32 s11, s19, 28
	s_min_u32 s10, s10, s11
	s_cmp_lt_u32 s10, 6
	s_cselect_b64 s[10:11], -1, 0
	s_or_b64 s[8:9], s[10:11], s[8:9]
	s_or_b64 s[2:3], s[8:9], s[2:3]
	s_or_b64 s[10:11], s[2:3], s[6:7]
	s_or_b64 s[12:13], s[14:15], s[10:11]
	v_or_b32_e32 v164, s35, v173
	v_cndmask_b32_e64 v0, 0, 1, s[12:13]
	v_cmp_ne_u32_e64 s[10:11], 1, v0
	s_andn2_b64 vcc, exec, s[12:13]
	v_ashrrev_i32_e32 v165, 31, v164
	s_cbranch_vccnz .LBB0_205
	v_lshlrev_b64 v[130:131], 7, v[164:165]
	v_lshl_add_u64 v[132:133], v[154:155], 0, v[130:131]
	v_lshl_add_u64 v[130:131], v[152:153], 0, v[130:131]
	flat_load_dwordx4 v[134:137], v[130:131]
	flat_load_dwordx4 v[224:227], v[130:131] offset:2048
	flat_load_dwordx4 v[228:231], v[132:133] offset:2048
	s_nop 0
	flat_load_dwordx4 v[130:133], v[132:133]
	s_branch .LBB0_206

;     __device__ __forceinline__ void operator()(const f32x4 (&acc)[2][2][4][2], const Unit& u, int wr, int wc, int fr, int fq, PG8_LAS unsigned char* lds) const {
;     ...
;                 if (anyrope) { cs = *(const f32x4*)(cosT + (size_t)row * 32 + 16 * gsub + 4 * fq); sn = *(const f32x4*)(sinT + (size_t)row * 32 + 16 * gsub + 4 * fq); }
.LBB0_239:
	v_mov_b32_e32 v134, v224
	v_mov_b32_e32 v135, v225
	v_mov_b32_e32 v136, v226
	v_mov_b32_e32 v137, v227
	v_mov_b32_e32 v130, v228
	v_mov_b32_e32 v131, v229
	v_mov_b32_e32 v132, v230
	v_mov_b32_e32 v133, v231
	s_branch .LBB0_243

;     __device__ __forceinline__ void operator()(const f32x4 (&acc)[2][2][4][2], const Unit& u, int wr, int wc, int fr, int fq, PG8_LAS unsigned char* lds) const {
;     ...
;                 if (anyrope) { cs = *(const f32x4*)(cosT + (size_t)row * 32 + 16 * gsub + 4 * fq); sn = *(const f32x4*)(sinT + (size_t)row * 32 + 16 * gsub + 4 * fq); }
.LBB0_276:
	v_lshlrev_b64 v[130:131], 7, v[160:161]
	v_lshl_add_u64 v[132:133], v[154:155], 0, v[130:131]
	v_lshl_add_u64 v[130:131], v[152:153], 0, v[130:131]
	flat_load_dwordx4 v[134:137], v[130:131]
	flat_load_dwordx4 v[224:227], v[130:131] offset:2048
	flat_load_dwordx4 v[228:231], v[132:133] offset:2048
	s_nop 0
	flat_load_dwordx4 v[130:133], v[132:133]
	s_branch .LBB0_280

;     __device__ __forceinline__ void operator()(const f32x4 (&acc)[2][2][4][2], const Unit& u, int wr, int wc, int fr, int fq, PG8_LAS unsigned char* lds) const {
;     ...
;                 if (anyrope) { cs = *(const f32x4*)(cosT + (size_t)row * 32 + 16 * gsub + 4 * fq); sn = *(const f32x4*)(sinT + (size_t)row * 32 + 16 * gsub + 4 * fq); }
.LBB0_424:
	v_lshlrev_b64 v[130:131], 7, v[182:183]
	v_lshl_add_u64 v[132:133], v[154:155], 0, v[130:131]
	v_lshl_add_u64 v[130:131], v[152:153], 0, v[130:131]
	flat_load_dwordx4 v[134:137], v[130:131]
	flat_load_dwordx4 v[224:227], v[130:131] offset:2048
	flat_load_dwordx4 v[228:231], v[132:133] offset:2048
	s_nop 0
	flat_load_dwordx4 v[130:133], v[132:133]
	s_branch .LBB0_428
